# attention loop: K-fragment prefetch depth 9 (10 register slots) using the freed staging registers
# baseline (speedup 1.0000x reference)
; __device__ __forceinline__ void attn_unit(LAS char* lds, const bf16_t* Qp, const bf16_t* KVp, const bf16_t* KRp, int ntiles, bf16_t* Yp, bool dry) {
;     ...
;         AT_QK(sb0, pa0, pa1);
;         AT_QK(sb0 + 1, pb0, pb1);
.Latt_noload:
	ds_read_b128 v[66:69], v0 offset:0
	ds_read_b128 v[70:73], v0 offset:6656
	ds_read_b128 v[74:77], v0 offset:32
	ds_read_b128 v[78:81], v0 offset:6688
	ds_read_b128 v[212:215], v0 offset:64
	ds_read_b128 v[240:243], v0 offset:6720
	ds_read_b128 v[244:247], v0 offset:96
	ds_read_b128 v[248:251], v0 offset:6752
	ds_read_b128 v[146:149], v0 offset:128
	s_waitcnt lgkmcnt(8)
	v_mfma_f32_32x32x16_bf16 v[114:129], v[66:69], v[154:157], v[82:97]
	ds_read_b128 v[150:153], v0 offset:6784
	s_waitcnt lgkmcnt(8)
	v_mfma_f32_32x32x16_bf16 v[98:113], v[70:73], v[154:157], v[82:97]
	ds_read_b128 v[66:69], v0 offset:160
	s_waitcnt lgkmcnt(8)
	v_mfma_f32_32x32x16_bf16 v[114:129], v[74:77], v[158:161], v[114:129]
	ds_read_b128 v[70:73], v0 offset:6816
	s_waitcnt lgkmcnt(8)
	v_mfma_f32_32x32x16_bf16 v[98:113], v[78:81], v[158:161], v[98:113]
	ds_read_b128 v[74:77], v0 offset:13312
	s_waitcnt lgkmcnt(8)
	v_mfma_f32_32x32x16_bf16 v[114:129], v[212:215], v[162:165], v[114:129]
	ds_read_b128 v[78:81], v0 offset:19968
	s_waitcnt lgkmcnt(8)
	v_mfma_f32_32x32x16_bf16 v[98:113], v[240:243], v[162:165], v[98:113]
	ds_read_b128 v[212:215], v0 offset:13344
	s_waitcnt lgkmcnt(8)
	v_mfma_f32_32x32x16_bf16 v[114:129], v[244:247], v[166:169], v[114:129]
	ds_read_b128 v[240:243], v0 offset:20000
	s_waitcnt lgkmcnt(8)
	v_mfma_f32_32x32x16_bf16 v[98:113], v[248:251], v[166:169], v[98:113]
	ds_read_b128 v[244:247], v0 offset:13376
	s_waitcnt lgkmcnt(8)
	v_mfma_f32_32x32x16_bf16 v[114:129], v[146:149], v[170:173], v[114:129]
	ds_read_b128 v[248:251], v0 offset:20032
	s_waitcnt lgkmcnt(8)
	v_mfma_f32_32x32x16_bf16 v[98:113], v[150:153], v[170:173], v[98:113]
	ds_read_b128 v[146:149], v0 offset:13408
	s_waitcnt lgkmcnt(8)
	v_mfma_f32_32x32x16_bf16 v[114:129], v[66:69], v[174:177], v[114:129]
	ds_read_b128 v[150:153], v0 offset:20064
	s_waitcnt lgkmcnt(8)
	v_mfma_f32_32x32x16_bf16 v[98:113], v[70:73], v[174:177], v[98:113]
	ds_read_b128 v[66:69], v0 offset:13440
	s_waitcnt lgkmcnt(8)
	v_mfma_f32_32x32x16_bf16 v[2:17], v[74:77], v[154:157], v[82:97]
	ds_read_b128 v[70:73], v0 offset:20096
	s_waitcnt lgkmcnt(8)
	v_mfma_f32_32x32x16_bf16 v[18:33], v[78:81], v[154:157], v[82:97]
	ds_read_b128 v[74:77], v0 offset:13472
	s_waitcnt lgkmcnt(8)
	v_mfma_f32_32x32x16_bf16 v[2:17], v[212:215], v[158:161], v[2:17]
	ds_read_b128 v[78:81], v0 offset:20128
	s_waitcnt lgkmcnt(8)
	v_mfma_f32_32x32x16_bf16 v[18:33], v[240:243], v[158:161], v[18:33]
	ds_read_b64_tr_b16 v[216:217], v185 offset:53248
	ds_read_b64_tr_b16 v[218:219], v185 offset:53760
	s_waitcnt lgkmcnt(9)
	v_mfma_f32_32x32x16_bf16 v[2:17], v[244:247], v[162:165], v[2:17]
	ds_read_b64_tr_b16 v[220:221], v185 offset:57344
	ds_read_b64_tr_b16 v[222:223], v185 offset:57856
	s_waitcnt lgkmcnt(10)
	v_mfma_f32_32x32x16_bf16 v[18:33], v[248:251], v[162:165], v[18:33]
	ds_read_b64_tr_b16 v[224:225], v185 offset:54272
	ds_read_b64_tr_b16 v[226:227], v185 offset:54784
	s_waitcnt lgkmcnt(11)
	v_mfma_f32_32x32x16_bf16 v[2:17], v[146:149], v[166:169], v[2:17]
	ds_read_b64_tr_b16 v[228:229], v185 offset:58368
	ds_read_b64_tr_b16 v[230:231], v185 offset:58880
	s_waitcnt lgkmcnt(12)
	v_mfma_f32_32x32x16_bf16 v[18:33], v[150:153], v[166:169], v[18:33]
	ds_read_b64_tr_b16 v[232:233], v185 offset:55296
	ds_read_b64_tr_b16 v[234:235], v185 offset:55808
	s_waitcnt lgkmcnt(13)
	v_mfma_f32_32x32x16_bf16 v[2:17], v[66:69], v[170:173], v[2:17]
	ds_read_b64_tr_b16 v[236:237], v185 offset:59392
	ds_read_b64_tr_b16 v[238:239], v185 offset:59904
	s_waitcnt lgkmcnt(14)
	v_mfma_f32_32x32x16_bf16 v[18:33], v[70:73], v[170:173], v[18:33]
	ds_read_b64_tr_b16 v[240:241], v185 offset:56320
	s_waitcnt lgkmcnt(11)
	ds_read_b64_tr_b16 v[242:243], v185 offset:56832
	v_mfma_f32_32x32x16_bf16 v[2:17], v[74:77], v[174:177], v[2:17]
	ds_read_b64_tr_b16 v[244:245], v185 offset:60416
	ds_read_b64_tr_b16 v[246:247], v185 offset:60928
	v_mfma_f32_32x32x16_bf16 v[18:33], v[78:81], v[174:177], v[18:33]
	s_cmp_lg_u32 s35, 34
	s_cbranch_scc1 .Latt_nogate
	s_mul_i32 s14, s28, 0x1c00
	s_mul_hi_u32 s15, s25, 0x1c00
	s_add_i32 s15, s15, s14
	s_mul_i32 s14, s25, 0x1c00
	s_add_u32 s14, s88, s14
	s_addc_u32 s15, s89, s15
	s_lshl_b32 s2, s34, 1
	s_add_u32 s14, s14, s2
	s_addc_u32 s15, s15, 0
	v_lshlrev_b32_e32 v146, 1, v196
	v_mov_b32_e32 v147, 0
	s_mov_b64 s[2:3], 0x1000
	v_lshl_add_u64 v[146:147], s[14:15], 0, v[146:147]
	v_lshrrev_b32_e32 v148, 3, v191
	v_lshl_add_u64 v[146:147], v[146:147], 0, s[2:3]
	v_or_b32_e32 v148, s24, v148
	v_mad_i64_i32 v[150:151], s[16:17], v148, s13, v[146:147]
	v_or_b32_e32 v149, 8, v148
	global_load_dwordx4 v[130:133], v[150:151], off
	v_mad_i64_i32 v[152:153], s[16:17], v149, s13, v[146:147]
	v_or_b32_e32 v149, 16, v148
	global_load_dwordx4 v[134:137], v[152:153], off
	v_mad_i64_i32 v[150:151], s[16:17], v149, s13, v[146:147]
	v_or_b32_e32 v149, 24, v148
	global_load_dwordx4 v[138:141], v[150:151], off
	v_mad_i64_i32 v[152:153], s[16:17], v149, s13, v[146:147]
	s_nop 0
	global_load_dwordx4 v[142:145], v[152:153], off
.Latt_nogate:
	v_exp_f32_e32 v114, v114
	v_exp_f32_e32 v115, v115
	v_exp_f32_e32 v116, v116
	v_exp_f32_e32 v117, v117
	v_exp_f32_e32 v118, v118
	v_exp_f32_e32 v119, v119
	v_exp_f32_e32 v120, v120
	v_exp_f32_e32 v121, v121
	v_cvt_pk_bf16_f32 v66, v114, v115
	v_cvt_pk_bf16_f32 v67, v116, v117
	v_cvt_pk_bf16_f32 v68, v118, v119
	v_cvt_pk_bf16_f32 v69, v120, v121
	v_add_f32_e32 v178, v114, v115
	v_add_f32_e32 v179, v116, v117
	v_add_f32_e32 v180, v118, v119
	v_add_f32_e32 v181, v120, v121
	v_add_f32_e32 v178, v178, v179
	v_add_f32_e32 v180, v180, v181
	v_add_f32_e32 v178, v178, v180
	v_add_f32_e32 v210, v210, v178
	ds_read_b64_tr_b16 v[114:115], v184 offset:53248
	s_waitcnt lgkmcnt(11)
	ds_read_b64_tr_b16 v[116:117], v184 offset:53760
	ds_read_b64_tr_b16 v[118:119], v184 offset:57344
	ds_read_b64_tr_b16 v[120:121], v184 offset:57856
	v_exp_f32_e32 v122, v122
	v_exp_f32_e32 v123, v123
	v_exp_f32_e32 v124, v124
	v_mfma_f32_32x32x16_bf16 v[34:49], v[66:69], v[216:219], v[34:49]
	v_exp_f32_e32 v125, v125
	v_exp_f32_e32 v126, v126
	v_exp_f32_e32 v127, v127
	v_exp_f32_e32 v128, v128
	v_exp_f32_e32 v129, v129
	v_cvt_pk_bf16_f32 v70, v122, v123
	v_cvt_pk_bf16_f32 v71, v124, v125
	v_mfma_f32_32x32x16_bf16 v[50:65], v[66:69], v[220:223], v[50:65]
	v_cvt_pk_bf16_f32 v72, v126, v127
	v_cvt_pk_bf16_f32 v73, v128, v129
	v_add_f32_e32 v178, v122, v123
	v_add_f32_e32 v179, v124, v125
	v_add_f32_e32 v180, v126, v127
	v_add_f32_e32 v181, v128, v129
	v_add_f32_e32 v178, v178, v179
	v_add_f32_e32 v180, v180, v181
	v_add_f32_e32 v178, v178, v180
	v_add_f32_e32 v210, v210, v178
	ds_read_b64_tr_b16 v[122:123], v184 offset:54272
	s_waitcnt lgkmcnt(11)
	ds_read_b64_tr_b16 v[124:125], v184 offset:54784
	ds_read_b64_tr_b16 v[126:127], v184 offset:58368
	ds_read_b64_tr_b16 v[128:129], v184 offset:58880
	v_exp_f32_e32 v98, v98
	v_exp_f32_e32 v99, v99
	v_exp_f32_e32 v100, v100
	v_mfma_f32_32x32x16_bf16 v[34:49], v[70:73], v[224:227], v[34:49]
	v_exp_f32_e32 v101, v101
	v_exp_f32_e32 v102, v102
	v_exp_f32_e32 v103, v103
	v_exp_f32_e32 v104, v104
	v_exp_f32_e32 v105, v105
	v_cvt_pk_bf16_f32 v74, v98, v99
	v_cvt_pk_bf16_f32 v75, v100, v101
	v_mfma_f32_32x32x16_bf16 v[50:65], v[70:73], v[228:231], v[50:65]
	v_cvt_pk_bf16_f32 v76, v102, v103
	v_cvt_pk_bf16_f32 v77, v104, v105
	v_add_f32_e32 v178, v98, v99
	v_add_f32_e32 v179, v100, v101
	v_add_f32_e32 v180, v102, v103
	v_add_f32_e32 v181, v104, v105
	v_add_f32_e32 v178, v178, v179
	v_add_f32_e32 v180, v180, v181
	v_add_f32_e32 v178, v178, v180
	v_add_f32_e32 v210, v210, v178
	ds_read_b64_tr_b16 v[98:99], v184 offset:55296
	s_waitcnt lgkmcnt(11)
	ds_read_b64_tr_b16 v[100:101], v184 offset:55808
	ds_read_b64_tr_b16 v[102:103], v184 offset:59392
	ds_read_b64_tr_b16 v[104:105], v184 offset:59904
	v_exp_f32_e32 v106, v106
	v_exp_f32_e32 v107, v107
	v_exp_f32_e32 v108, v108
	v_mfma_f32_32x32x16_bf16 v[34:49], v[74:77], v[232:235], v[34:49]
	v_exp_f32_e32 v109, v109
	v_exp_f32_e32 v110, v110
	v_exp_f32_e32 v111, v111
	v_exp_f32_e32 v112, v112
	v_exp_f32_e32 v113, v113
	v_cvt_pk_bf16_f32 v78, v106, v107
	v_cvt_pk_bf16_f32 v79, v108, v109
	v_mfma_f32_32x32x16_bf16 v[50:65], v[74:77], v[236:239], v[50:65]
	v_cvt_pk_bf16_f32 v80, v110, v111
	v_cvt_pk_bf16_f32 v81, v112, v113
	v_add_f32_e32 v178, v106, v107
	v_add_f32_e32 v179, v108, v109
	v_add_f32_e32 v180, v110, v111
	v_add_f32_e32 v181, v112, v113
	v_add_f32_e32 v178, v178, v179
	v_add_f32_e32 v180, v180, v181
	v_add_f32_e32 v178, v178, v180
	v_add_f32_e32 v210, v210, v178
	ds_read_b64_tr_b16 v[106:107], v184 offset:56320
	s_waitcnt lgkmcnt(11)
	ds_read_b64_tr_b16 v[108:109], v184 offset:56832
	ds_read_b64_tr_b16 v[110:111], v184 offset:60416
	ds_read_b64_tr_b16 v[112:113], v184 offset:60928
	v_exp_f32_e32 v2, v2
	v_exp_f32_e32 v3, v3
	v_exp_f32_e32 v4, v4
	v_mfma_f32_32x32x16_bf16 v[34:49], v[78:81], v[240:243], v[34:49]
	v_exp_f32_e32 v5, v5
	v_exp_f32_e32 v6, v6
	v_exp_f32_e32 v7, v7
	v_exp_f32_e32 v8, v8
	v_exp_f32_e32 v9, v9
	v_cvt_pk_bf16_f32 v66, v2, v3
	v_cvt_pk_bf16_f32 v67, v4, v5
	v_mfma_f32_32x32x16_bf16 v[50:65], v[78:81], v[244:247], v[50:65]
	v_cvt_pk_bf16_f32 v68, v6, v7
	v_cvt_pk_bf16_f32 v69, v8, v9
	v_add_f32_e32 v178, v2, v3
	v_add_f32_e32 v179, v4, v5
	v_add_f32_e32 v180, v6, v7
	v_add_f32_e32 v181, v8, v9
	v_add_f32_e32 v178, v178, v179
	v_add_f32_e32 v180, v180, v181
	v_add_f32_e32 v178, v178, v180
	v_add_f32_e32 v210, v210, v178
	v_exp_f32_e32 v10, v10
	v_exp_f32_e32 v11, v11
	v_exp_f32_e32 v12, v12
	v_mfma_f32_32x32x16_bf16 v[34:49], v[66:69], v[114:117], v[34:49]
	v_exp_f32_e32 v13, v13
	v_exp_f32_e32 v14, v14
	v_exp_f32_e32 v15, v15
	v_exp_f32_e32 v16, v16
	v_exp_f32_e32 v17, v17
	v_cvt_pk_bf16_f32 v70, v10, v11
	v_cvt_pk_bf16_f32 v71, v12, v13
	s_waitcnt lgkmcnt(12)
	v_mfma_f32_32x32x16_bf16 v[50:65], v[66:69], v[118:121], v[50:65]
	v_cvt_pk_bf16_f32 v72, v14, v15
	v_cvt_pk_bf16_f32 v73, v16, v17
	v_add_f32_e32 v178, v10, v11
	v_add_f32_e32 v179, v12, v13
	v_add_f32_e32 v180, v14, v15
	v_add_f32_e32 v181, v16, v17
	v_add_f32_e32 v178, v178, v179
	v_add_f32_e32 v180, v180, v181
	v_add_f32_e32 v178, v178, v180
	v_add_f32_e32 v210, v210, v178
	v_exp_f32_e32 v18, v18
	v_exp_f32_e32 v19, v19
	v_exp_f32_e32 v20, v20
	s_waitcnt lgkmcnt(10)
	v_mfma_f32_32x32x16_bf16 v[34:49], v[70:73], v[122:125], v[34:49]
	v_exp_f32_e32 v21, v21
	v_exp_f32_e32 v22, v22
	v_exp_f32_e32 v23, v23
	v_exp_f32_e32 v24, v24
	v_exp_f32_e32 v25, v25
	v_cvt_pk_bf16_f32 v74, v18, v19
	v_cvt_pk_bf16_f32 v75, v20, v21
	s_waitcnt lgkmcnt(8)
	v_mfma_f32_32x32x16_bf16 v[50:65], v[70:73], v[126:129], v[50:65]
	v_cvt_pk_bf16_f32 v76, v22, v23
	v_cvt_pk_bf16_f32 v77, v24, v25
	v_add_f32_e32 v178, v18, v19
	v_add_f32_e32 v179, v20, v21
	v_add_f32_e32 v180, v22, v23
	v_add_f32_e32 v181, v24, v25
	v_add_f32_e32 v178, v178, v179
	v_add_f32_e32 v180, v180, v181
	v_add_f32_e32 v178, v178, v180
	v_add_f32_e32 v210, v210, v178
	v_exp_f32_e32 v26, v26
	v_exp_f32_e32 v27, v27
	v_exp_f32_e32 v28, v28
	s_waitcnt lgkmcnt(6)
	v_mfma_f32_32x32x16_bf16 v[34:49], v[74:77], v[98:101], v[34:49]
	v_exp_f32_e32 v29, v29
	v_exp_f32_e32 v30, v30
	v_exp_f32_e32 v31, v31
	v_exp_f32_e32 v32, v32
	v_exp_f32_e32 v33, v33
	v_cvt_pk_bf16_f32 v78, v26, v27
	v_cvt_pk_bf16_f32 v79, v28, v29
	s_waitcnt lgkmcnt(4)
	v_mfma_f32_32x32x16_bf16 v[50:65], v[74:77], v[102:105], v[50:65]
	v_cvt_pk_bf16_f32 v80, v30, v31
	v_cvt_pk_bf16_f32 v81, v32, v33
	v_add_f32_e32 v178, v26, v27
	v_add_f32_e32 v179, v28, v29
	v_add_f32_e32 v180, v30, v31
	v_add_f32_e32 v181, v32, v33
	v_add_f32_e32 v178, v178, v179
	v_add_f32_e32 v180, v180, v181
	v_add_f32_e32 v178, v178, v180
	v_add_f32_e32 v210, v210, v178
	s_waitcnt lgkmcnt(2)
	v_mfma_f32_32x32x16_bf16 v[34:49], v[78:81], v[106:109], v[34:49]
	s_waitcnt lgkmcnt(0)
	v_mfma_f32_32x32x16_bf16 v[50:65], v[78:81], v[110:113], v[50:65]
	s_cmp_eq_u32 s35, 0
	s_cbranch_scc1 .Latt_rs
	v_cmp_lt_f32_e32 vcc, 0x4b800000, v210
	s_cbranch_vccnz .Latt_rs
